# speedup vs baseline: 1.0135x; 1.0135x over previous
; __device__ __forceinline__ void build_ctab(char* lds, const float* LFbh, const int tid) {
;     const int lane = tid & 63, wid = tid >> 6;
;     float* ctab = (float*)(lds + OFF_C); float* red = (float*)(lds + OFF_RED);
;     constexpr int PER = 9; const int e0 = tid * PER;
;     float v[PER]; float s = 0.f;
; #pragma unroll
;     for (int i = 0; i < PER; ++i) { const int kk = e0 + i; float x = 0.f; if (kk >= 48 && kk < KVROWS) x = LFbh[kk]; s += x; v[i] = s; }
;     float incl = s;
; #pragma unroll
;     for (int off = 1; off < 64; off <<= 1) { const float t = __shfl_up(incl, off); if (lane >= off) incl += t; }
;     if (lane == 63) red[wid] = incl;
;     __syncthreads();
;     float base = incl - s;
;     for (int w = 0; w < wid; ++w) base += red[w];
; #pragma unroll
;     for (int i = 0; i < PER; ++i) { const int kk = e0 + i; if (kk < KVROWS) ctab[kk] = -(base + v[i]); }
;     __syncthreads();
; }
; __device__ __forceinline__ void attn_phase(char* lds, const Tensors& T, int vcu, int G) {
;     for (int L = vcu; L < NB * NH * 8; L += G) {
;         const int bh = L >> 3, x = L & 7, b = bh >> 4, h = bh & 15;
;         int tid = threadIdx.x; asm volatile("" : "+v"(tid));
;         build_ctab(lds, T.LF + (size_t)(b * NH + h) * KVROWS, tid);
;         const BlockRef r0 = mkref(T, b, h, 15 - x), r1 = mkref(T, b, h, x);
;         Seam S;
.LBB0_482:
	v_readlane_b32 s2, v248, 0
	v_readlane_b32 s4, v248, 29
	v_readlane_b32 s3, v248, 1
	s_cmp_lt_i32 s2, 3
	v_readlane_b32 s10, v248, 35
	s_cselect_b64 s[2:3], -1, 0
	v_readlane_b32 s11, v248, 36
	s_add_u32 s4, s10, 0x18d00000
	v_readlane_b32 s5, v248, 30
	v_readlane_b32 s6, v248, 31
	v_readlane_b32 s7, v248, 32
	v_readlane_b32 s8, v248, 33
	v_readlane_b32 s9, v248, 34
	v_writelane_b32 v248, s4, 54
	s_addc_u32 s4, s11, 0
	v_writelane_b32 v248, s4, 56
	s_add_u32 s4, s10, 0x1ad00000
	s_addc_u32 s5, s11, 0
	v_writelane_b32 v248, s4, 57
	s_and_b64 s[0:1], s[2:3], s[0:1]
	s_nop 0
	v_writelane_b32 v248, s5, 58
	v_writelane_b32 v248, s0, 59
	s_andn2_b64 vcc, exec, s[0:1]
	s_nop 0
	v_writelane_b32 v248, s1, 60
	s_cbranch_vccnz .LBB0_601
	s_cmpk_gt_i32 s60, 0xff
	s_cbranch_scc1 .LBB0_590
	s_lshl_b32 s0, s60, 8
	v_writelane_b32 v248, s0, 61
	s_lshl_b32 s0, s96, 8
	v_writelane_b32 v248, s0, 62
	s_mov_b32 s1, 0
	v_writelane_b32 v248, s0, 63
	v_mbcnt_lo_u32_b32 v0, -1, 0
	v_mbcnt_hi_u32_b32 v180, -1, v0
	v_writelane_b32 v247, s1, 0
	s_add_i32 s0, 0, 0x1c900
	v_writelane_b32 v247, s0, 1
	s_add_i32 s0, 0, 0x18800
	v_writelane_b32 v247, s0, 2
	s_add_i32 s0, 0, 0x18900
	v_writelane_b32 v247, s0, 3
	v_writelane_b32 v247, s66, 4
	s_movk_i32 s6, 0x1010
	v_mov_b32_e32 v129, 0
	v_writelane_b32 v247, s67, 5
	v_writelane_b32 v247, s68, 6
	v_and_b32_e32 v181, 64, v180
	v_add_u32_e32 v182, -1, v180
	v_writelane_b32 v247, s69, 7
	v_writelane_b32 v247, s97, 8
	v_add_u32_e32 v183, -2, v180
	v_add_u32_e32 v184, -4, v180
	v_add_u32_e32 v185, -8, v180
	v_add_u32_e32 v187, -16, v180
	v_subrev_u32_e32 v188, 32, v180
	s_mov_b32 s33, 0x42800000
	s_mov_b64 s[80:81], 0xaa0c000
	s_mov_b64 s[84:85], 0xcb08000
	s_mov_b64 s[74:75], 0xaa10000
	s_mov_b64 s[94:95], 0xcb0c000
	v_mov_b32_e32 v189, 0xf149f2ca
	v_mov_b32_e32 v130, 0xff800000
	v_mov_b32_e32 v190, 0x80
	v_writelane_b32 v247, s96, 9
	v_writelane_b32 v247, s93, 10
	s_branch .LBB0_486
